# phase 0 weight transposes rewritten by hand as one engine: two items of loads in flight, LDS tile double-buffered, one barrier per item
# baseline (speedup 1.0000x reference)
.LBB0_20:
	s_or_b64 exec, exec, s[2:3]
	s_cmp_lt_i32 s76, 1
	s_cselect_b64 s[0:1], -1, 0
	s_cmp_gt_i32 s77, 0
	s_cselect_b64 s[2:3], -1, 0
	s_and_b64 s[12:13], s[0:1], s[2:3]
	s_andn2_b64 vcc, exec, s[12:13]
	s_cbranch_vccnz .LBB0_81
	v_mov_b32_e32 v6, v188
	s_cmpk_gt_i32 s33, 0xd5b
	s_cbranch_scc1 .LBB0_81
	s_mov_b32 s98, 0
	s_mov_b32 s99, 0
	s_mov_b32 s101, 0
	v_mov_b32_e32 v0, 0xff95f800
	v_lshl_add_u32 v14, v6, 2, v0
	v_and_b32_e32 v0, 15, v6
	v_cvt_f32_ubyte0_e32 v0, v0
	v_writelane_b32 v250, s94, 3
	s_movk_i32 s0, 0x800
	v_mul_f32_e32 v7, 0xbd800000, v0
	v_writelane_b32 v250, s95, 4
	v_cmp_gt_i32_e64 s[0:1], s0, v6
	v_mov_b32_e32 v0, 0x461c4000
	v_cmp_eq_f32_e32 vcc, 0, v7
	v_writelane_b32 v250, s0, 5
	s_movk_i32 s2, 0x204
	v_cndmask_b32_e64 v12, v0, 1.0, vcc
	v_writelane_b32 v250, s1, 6
	v_frexp_mant_f32_e32 v0, v12
	s_mov_b32 s0, 0x3f2aaaab
	v_cmp_gt_f32_e64 s[4:5], s0, v0
	s_mov_b32 s0, 0x3f317218
	s_mov_b32 s35, 0x42b17218
	v_cndmask_b32_e64 v1, 1.0, 2.0, s[4:5]
	v_mul_f32_e32 v0, v0, v1
	v_add_f32_e32 v3, 1.0, v0
	v_rcp_f32_e32 v10, v3
	v_add_f32_e32 v1, -1.0, v3
	v_sub_f32_e32 v5, v0, v1
	v_add_f32_e32 v1, -1.0, v0
	v_mul_f32_e32 v11, v1, v10
	v_mul_f32_e32 v2, v3, v11
	v_fma_f32 v4, v11, v3, -v2
	v_fmac_f32_e32 v4, v11, v5
	v_add_f32_e32 v0, v2, v4
	v_sub_f32_e32 v3, v1, v0
	v_pk_add_f32 v[8:9], v[0:1], v[2:3] neg_lo:[0,1] neg_hi:[0,1]
	v_mov_b32_e32 v5, v0
	v_pk_add_f32 v[0:1], v[8:9], v[4:5] neg_lo:[0,1] neg_hi:[0,1]
	v_mov_b32_e32 v4, 0x3e91f4c4
	v_add_f32_e32 v0, v0, v1
	v_add_f32_e32 v0, v3, v0
	v_mul_f32_e32 v1, v10, v0
	v_add_f32_e32 v0, v11, v1
	v_sub_f32_e32 v2, v0, v11
	v_sub_f32_e32 v13, v1, v2
	v_mul_f32_e32 v1, v0, v0
	v_fma_f32 v3, v0, v0, -v1
	v_add_f32_e32 v2, v13, v13
	v_fmac_f32_e32 v3, v0, v2
	v_add_f32_e32 v2, v1, v3
	v_fmac_f32_e32 v4, 0x3e76c4e1, v2
	v_fmaak_f32 v4, v2, v4, 0x3ecccdef
	v_sub_f32_e32 v1, v2, v1
	v_sub_f32_e32 v15, v3, v1
	v_mul_f32_e32 v1, v2, v4
	v_fma_f32 v3, v2, v4, -v1
	v_fmac_f32_e32 v3, v15, v4
	v_add_f32_e32 v4, v1, v3
	v_add_f32_e32 v5, 0x3f2aaaaa, v4
	v_sub_f32_e32 v1, v4, v1
	v_sub_f32_e32 v1, v3, v1
	v_add_f32_e32 v3, 0xbf2aaaaa, v5
	v_add_f32_e32 v1, 0x31739010, v1
	v_sub_f32_e32 v3, v4, v3
	v_pk_mul_f32 v[8:9], v[0:1], v[2:3]
	v_pk_add_f32 v[10:11], v[0:1], v[2:3]
	v_fma_f32 v4, v2, v0, -v8
	v_fmac_f32_e32 v4, v2, v13
	v_mov_b32_e32 v9, v11
	v_fmac_f32_e32 v4, v15, v0
	v_pk_add_f32 v[2:3], v[8:9], v[4:5]
	v_ldexp_f32 v15, v13, 1
	v_sub_f32_e32 v1, v2, v8
	v_sub_f32_e32 v1, v4, v1
	v_sub_f32_e32 v4, v5, v3
	v_add_f32_e32 v9, v11, v4
	v_pk_mul_f32 v[4:5], v[2:3], v[2:3] op_sel:[0,1] op_sel_hi:[1,0]
	v_cvt_f64_f32_e32 v[10:11], v12
	v_frexp_exp_i32_f64_e32 v5, v[10:11]
	v_subbrev_co_u32_e64 v5, s[4:5], 0, v5, s[4:5]
	v_cvt_f32_i32_e32 v5, v5
	v_fma_f32 v8, v2, v3, -v4
	v_fmac_f32_e32 v8, v2, v9
	v_fmac_f32_e32 v8, v1, v3
	v_mul_f32_e32 v2, 0x3f317218, v5
	v_fma_f32 v1, v5, s0, -v2
	v_fmamk_f32 v10, v5, 0xb102e308, v1
	v_ldexp_f32 v11, v0, 1
	v_add_f32_e32 v3, v4, v8
	v_pk_add_f32 v[0:1], v[2:3], v[10:11]
	v_mov_b32_e32 v12, v3
	v_mov_b32_e32 v13, v1
	v_mov_b32_e32 v5, v11
	v_pk_add_f32 v[4:5], v[12:13], v[4:5] neg_lo:[0,1] neg_hi:[0,1]
	v_mov_b32_e32 v9, v3
	v_pk_add_f32 v[4:5], v[8:9], v[4:5] neg_lo:[0,1] neg_hi:[0,1]
	v_mov_b32_e32 v11, v0
	v_add_f32_e32 v3, v15, v4
	v_add_f32_e32 v3, v3, v5
	v_pk_add_f32 v[4:5], v[0:1], v[2:3] neg_lo:[0,1] neg_hi:[0,1]
	v_pk_add_f32 v[8:9], v[0:1], v[2:3]
	v_mov_b32_e32 v2, v3
	v_mov_b32_e32 v5, v9
	v_pk_add_f32 v[12:13], v[10:11], v[4:5] neg_lo:[0,1] neg_hi:[0,1]
	v_pk_add_f32 v[4:5], v[10:11], v[4:5]
	v_mov_b32_e32 v3, v0
	v_pk_add_f32 v[10:11], v[4:5], v[0:1] op_sel:[1,0] op_sel_hi:[0,1] neg_lo:[0,1] neg_hi:[0,1]
	v_pk_add_f32 v[16:17], v[8:9], v[10:11] op_sel_hi:[1,0] neg_lo:[0,1] neg_hi:[0,1]
	v_mov_b32_e32 v8, v9
	v_mov_b32_e32 v9, v5
	v_pk_mov_b32 v[10:11], v[0:1], v[10:11] op_sel:[1,0]
	v_mov_b32_e32 v16, v12
	v_pk_add_f32 v[8:9], v[8:9], v[10:11] neg_lo:[0,1] neg_hi:[0,1]
	v_mov_b32_e32 v13, v5
	v_pk_add_f32 v[0:1], v[2:3], v[8:9] neg_lo:[0,1] neg_hi:[0,1]
	s_mov_b32 s1, 0x3fb8aa3b
	v_pk_add_f32 v[2:3], v[16:17], v[0:1]
	s_add_u32 s14, s74, 0x5000
	v_pk_add_f32 v[8:9], v[2:3], v[2:3] op_sel:[0,1] op_sel_hi:[1,0]
	s_addc_u32 s15, s75, 0
	v_pk_add_f32 v[4:5], v[4:5], v[8:9] op_sel:[1,0] op_sel_hi:[0,1]
	v_mov_b32_e32 v3, v4
	v_pk_add_f32 v[10:11], v[2:3], v[12:13] neg_lo:[0,1] neg_hi:[0,1]
	v_mov_b32_e32 v1, v8
	v_sub_f32_e32 v2, v2, v10
	v_pk_add_f32 v[0:1], v[0:1], v[10:11] neg_lo:[0,1] neg_hi:[0,1]
	v_sub_f32_e32 v2, v12, v2
	v_add_f32_e32 v0, v0, v2
	v_add_f32_e32 v0, v0, v1
	v_add_f32_e32 v1, v4, v0
	v_sub_f32_e32 v2, v1, v4
	v_sub_f32_e32 v0, v0, v2
	v_mul_f32_e32 v2, v7, v1
	v_fma_f32 v1, v7, v1, -v2
	v_fmac_f32_e32 v1, v7, v0
	v_add_f32_e32 v0, v2, v1
	v_cmp_class_f32_e64 s[4:5], v2, s2
	v_sub_f32_e32 v3, v0, v2
	v_sub_f32_e32 v1, v1, v3
	v_cndmask_b32_e64 v0, v0, v2, s[4:5]
	v_mov_b32_e32 v2, 0x37000000
	v_cmp_eq_f32_e64 s[4:5], s35, v0
	s_add_u32 s16, s74, 0x27000
	s_addc_u32 s17, s75, 0
	v_cndmask_b32_e64 v2, 0, v2, s[4:5]
	v_sub_f32_e32 v3, v0, v2
	v_mul_f32_e32 v4, 0x3fb8aa3b, v3
	v_fma_f32 v5, v3, s1, -v4
	v_rndne_f32_e32 v8, v4
	v_fmac_f32_e32 v5, 0x32a5705f, v3
	v_sub_f32_e32 v4, v4, v8
	v_add_f32_e32 v4, v4, v5
	v_exp_f32_e32 v4, v4
	v_cvt_i32_f32_e32 v5, v8
	s_add_u32 s18, s74, 0x1905000
	s_mov_b32 s0, 0x7f800000
	s_addc_u32 s19, s75, 0
	v_cmp_neq_f32_e64 s[4:5], |v0|, s0
	s_mov_b32 s0, 0xc2ce8ed0
	s_add_u32 s20, s74, 0xe05000
	v_cndmask_b32_e64 v0, 0, v1, s[4:5]
	v_ldexp_f32 v1, v4, v5
	v_cmp_ngt_f32_e64 s[4:5], s0, v3
	s_addc_u32 s21, s75, 0
	v_mov_b32_e32 v15, 0x7f800000
	v_cndmask_b32_e64 v1, 0, v1, s[4:5]
	v_cmp_nlt_f32_e64 s[4:5], s35, v3
	s_add_u32 s22, s74, 0xc05000
	v_add_f32_e32 v0, v2, v0
	v_cndmask_b32_e64 v1, v15, v1, s[4:5]
	s_addc_u32 s23, s75, 0
	v_fma_f32 v0, v1, v0, v1
	v_cmp_class_f32_e64 s[4:5], v1, s2
	v_cmp_neq_f32_e64 s[0:1], v7, |v7|
	s_add_u32 s24, s74, 0x585000
	v_cndmask_b32_e64 v0, v0, v1, s[4:5]
	v_cndmask_b32_e64 v1, v15, 0, s[0:1]
	s_addc_u32 s25, s75, 0
	v_cndmask_b32_e64 v1, v1, 1.0, vcc
	v_cmp_class_f32_e64 s[0:1], v7, s2
	v_ashrrev_i32_e32 v7, 31, v6
	s_add_u32 s26, s48, 0x2a000
	v_cndmask_b32_e64 v16, |v0|, v1, s[0:1]
	v_lshl_add_u64 v[0:1], v[6:7], 3, s[74:75]
	s_mov_b64 s[0:1], 0x23000
	v_mov_b32_e32 v11, 0
	v_cmp_eq_u32_e64 s[6:7], 0, v6
	v_lshl_add_u64 v[8:9], v[0:1], 0, s[0:1]
	s_addc_u32 s27, s49, 0
	s_lshl_b32 s96, s33, 5
	s_lshl_b32 s97, s78, 5
	s_mov_b32 s93, 0xfe5163ab
	s_mov_b32 s28, 0x3c439041
	s_mov_b32 s29, 0xdb629599
	s_mov_b32 s94, 0xf534ddc0
	s_mov_b32 s95, 0xfc2757d1
	s_mov_b32 s2, 0x4e441529
	s_mov_b32 s3, 0xa2f9836e
	s_mov_b32 s0, 0x3fc90fda
	s_mov_b32 s1, 0xbfc90fda
	v_mov_b32_e32 v7, 0x3c0881c4
	v_mov_b32_e32 v17, 0xbab64f3b
	s_movk_i32 s4, 0x110
	s_movk_i32 s5, 0x5800
	s_movk_i32 s38, 0x3080
	v_mov_b32_e32 v24, v11
	v_mov_b32_e32 v25, v11
	v_mov_b32_e32 v26, v11
	v_mov_b32_e32 v27, v11
	v_not_b32_e32 v18, 63
	v_not_b32_e32 v19, 31
	v_mov_b32_e32 v20, 0x7fc00000
	s_mov_b32 s39, s33
	s_mov_b32 s31, 0
	v_writelane_b32 v250, s6, 7
	s_mov_b32 s34, 0x3e000000
	s_nop 0
	v_writelane_b32 v250, s7, 8
	s_branch .LBB0_25

.LBB0_57:
.LBB0_60:
.LBB0_63:
.LBB0_66:
	s_andn2_b64 vcc, exec, s[6:7]
	s_cbranch_vccnz .LBB0_72
	v_mov_b32_e32 v40, v188
	v_lshrrev_b32_e32 v41, 4, v40
	v_and_b32_e32 v43, 15, v40
	v_lshlrev_b32_e32 v42, 4, v43
	v_lshlrev_b32_e32 v43, 2, v43
	v_lshrrev_b32_e32 v44, 3, v40
	v_and_b32_e32 v45, 7, v40
	v_lshlrev_b32_e32 v45, 4, v45
	v_mov_b32_e32 v95, 0
	s_cmp_eq_u32 s98, 0
	s_cbranch_scc0 .Ltr_steady
	s_mov_b32 s30, s39
	s_mov_b32 s49, 0
	s_mov_b32 s91, 3
	s_branch .Ltr_fill
.Ltr_steady:
	s_mul_i32 s30, s78, 2
	s_add_i32 s30, s39, s30
	s_add_i32 s49, s99, 2
	s_cmp_ge_u32 s49, 3
	s_cbranch_scc0 .Ltr_slotok
	s_sub_i32 s49, s49, 3
.Ltr_slotok:
	s_mov_b32 s91, 1
.Ltr_fill:
	s_cmpk_lt_u32 s30, 0xd40
	s_cselect_b32 s30, s30, s39
	s_cmpk_lt_u32 s30, 0x400
	s_cbranch_scc1 .Ltr_w0
	s_cmpk_lt_u32 s30, 0x500
	s_cbranch_scc1 .Ltr_w1
	s_cmpk_lt_u32 s30, 0xa80
	s_cbranch_scc1 .Ltr_w2
	s_sub_i32 s6, s30, 0xa80
	s_mul_i32 s7, s6, 0x5d2
	s_lshr_b32 s7, s7, 16
	s_mul_i32 s8, s7, 44
	s_sub_i32 s8, s6, s8
	s_lshl_b32 s8, s8, 6
	s_lshl_b32 s7, s7, 6
	s_mov_b32 s6, s7
	s_mov_b64 s[10:11], s[86:87]
	s_mov_b32 s9, 0x1000
	s_mov_b32 s36, 0x1905000
	s_movk_i32 s48, 0x1600
	s_branch .Ltr_dec
.Ltr_w0:
	s_sub_i32 s6, s30, 0xc0
	s_and_b32 s8, s6, 15
	s_lshl_b32 s8, s8, 6
	s_lshr_b32 s7, s6, 4
	s_lshl_b32 s7, s7, 6
	s_mov_b32 s6, s7
	s_cmpk_lt_u32 s7, 0x600
	s_cbranch_scc1 .Ltr_w0b
	s_add_i32 s6, s7, 32
	s_cmpk_lt_u32 s7, 0xc00
	s_cbranch_scc1 .Ltr_w0b
	s_movk_i32 s6, 0x600
	s_cmpk_eq_u32 s7, 0xc00
	s_cbranch_scc1 .Ltr_w0b
	s_mov_b32 s6, 0
.Ltr_w0b:
	s_mov_b64 s[10:11], s[54:55]
	s_movk_i32 s9, 0x3080
	s_mov_b32 s36, 0x585000
	s_movk_i32 s48, 0x800
	s_branch .Ltr_dec
.Ltr_w1:
	s_sub_i32 s6, s30, 0x400
	s_and_b32 s8, s6, 15
	s_lshl_b32 s8, s8, 6
	s_lshr_b32 s7, s6, 4
	s_lshl_b32 s7, s7, 6
	s_mov_b32 s6, s7
	s_mov_b64 s[10:11], s[80:81]
	s_mov_b32 s9, 0x1000
	s_mov_b32 s36, 0xc05000
	s_movk_i32 s48, 0x800
	s_branch .Ltr_dec
.Ltr_w2:
	s_sub_i32 s6, s30, 0x500
	s_and_b32 s8, s6, 15
	s_lshl_b32 s8, s8, 6
	s_lshr_b32 s7, s6, 4
	s_lshl_b32 s7, s7, 6
	s_bfe_u32 s6, s7, 0x10007
	s_mul_i32 s6, s6, 0xb00
	s_lshr_b32 s37, s7, 8
	s_lshl_b32 s37, s37, 7
	s_add_i32 s6, s6, s37
	s_and_b32 s37, s7, 0x7f
	s_add_i32 s6, s6, s37
	s_mov_b64 s[10:11], s[84:85]
	s_movk_i32 s9, 0x5800
	s_mov_b32 s36, 0xe05000
	s_movk_i32 s48, 0x800
.Ltr_dec:
	s_mul_i32 s37, s8, s9
	s_lshl_b32 s6, s6, 2
	s_add_u32 s37, s37, s6
	s_add_u32 s10, s10, s37
	s_addc_u32 s11, s11, 0
	s_lshl_b32 s37, s9, 5
	s_add_u32 s88, s10, s37
	s_addc_u32 s89, s11, 0
	v_mul_lo_u32 v46, v41, s9
	v_add_u32_e32 v46, v46, v42
	s_mul_i32 s37, s7, s48
	s_lshl_b32 s6, s8, 1
	s_add_u32 s37, s37, s6
	s_add_u32 s36, s36, s37
	s_addc_u32 s37, 0, 0
	s_add_u32 s36, s74, s36
	s_addc_u32 s37, s75, s37
	v_mul_lo_u32 v94, v44, s48
	v_add_u32_e32 v94, v94, v45
	v_mov_b32_e32 v92, s36
	v_mov_b32_e32 v93, s37
	v_lshl_add_u64 v[92:93], v[92:93], 0, v[94:95]
	s_cmp_eq_u32 s49, 0
	s_cbranch_scc0 .Ltr_ld1
	global_load_dwordx4 v[60:63], v46, s[10:11]
	global_load_dwordx4 v[64:67], v46, s[88:89]
	v_mov_b32_e32 v84, v92
	v_mov_b32_e32 v85, v93
	s_branch .Ltr_ldone
.Ltr_ld1:
	s_cmp_eq_u32 s49, 1
	s_cbranch_scc0 .Ltr_ld2
	global_load_dwordx4 v[68:71], v46, s[10:11]
	global_load_dwordx4 v[72:75], v46, s[88:89]
	v_mov_b32_e32 v86, v92
	v_mov_b32_e32 v87, v93
	s_branch .Ltr_ldone
.Ltr_ld2:
	global_load_dwordx4 v[76:79], v46, s[10:11]
	global_load_dwordx4 v[80:83], v46, s[88:89]
	v_mov_b32_e32 v88, v92
	v_mov_b32_e32 v89, v93
.Ltr_ldone:
	s_add_i32 s91, s91, -1
	s_cmp_eq_u32 s91, 0
	s_cbranch_scc1 .Ltr_filled
	s_add_i32 s30, s30, s78
	s_add_i32 s49, s49, 1
	s_branch .Ltr_fill
.Ltr_filled:
	s_movk_i32 s6, 0x40
	s_mov_b32 s7, 1.0
	s_cmpk_lt_u32 s39, 0x400
	s_cbranch_scc0 .Ltr_nomask
	s_sub_i32 s8, s39, 0xc0
	s_lshr_b32 s8, s8, 4
	s_cmp_lt_u32 s8, 4
	s_cselect_b32 s7, 0x3e000000, s7
	s_cmp_lt_u32 s8, 48
	s_cbranch_scc1 .Ltr_nomask
	s_cmp_eq_u32 s8, 48
	s_cselect_b32 s6, 32, 0
.Ltr_nomask:
	v_cmp_gt_u32_e64 s[10:11], s6, v43
	s_cmp_eq_u32 s98, 0
	s_cbranch_scc0 .Ltr_wt1
	s_waitcnt vmcnt(4)
	s_branch .Ltr_wdone
.Ltr_wt1:
	s_cmp_eq_u32 s98, 1
	s_cbranch_scc0 .Ltr_wt2
	s_waitcnt vmcnt(5)
	s_branch .Ltr_wdone
.Ltr_wt2:
	s_waitcnt vmcnt(6)
.Ltr_wdone:
	s_cmp_eq_u32 s99, 0
	s_cbranch_scc0 .Ltr_mv1
	v_mul_f32_e32 v96, s7, v60
	v_mul_f32_e32 v97, s7, v61
	v_mul_f32_e32 v98, s7, v62
	v_mul_f32_e32 v99, s7, v63
	v_mul_f32_e32 v100, s7, v64
	v_mul_f32_e32 v101, s7, v65
	v_mul_f32_e32 v102, s7, v66
	v_mul_f32_e32 v103, s7, v67
	v_mov_b32_e32 v104, v84
	v_mov_b32_e32 v105, v85
	s_branch .Ltr_mvdone
.Ltr_mv1:
	s_cmp_eq_u32 s99, 1
	s_cbranch_scc0 .Ltr_mv2
	v_mul_f32_e32 v96, s7, v68
	v_mul_f32_e32 v97, s7, v69
	v_mul_f32_e32 v98, s7, v70
	v_mul_f32_e32 v99, s7, v71
	v_mul_f32_e32 v100, s7, v72
	v_mul_f32_e32 v101, s7, v73
	v_mul_f32_e32 v102, s7, v74
	v_mul_f32_e32 v103, s7, v75
	v_mov_b32_e32 v104, v86
	v_mov_b32_e32 v105, v87
	s_branch .Ltr_mvdone
.Ltr_mv2:
	v_mul_f32_e32 v96, s7, v76
	v_mul_f32_e32 v97, s7, v77
	v_mul_f32_e32 v98, s7, v78
	v_mul_f32_e32 v99, s7, v79
	v_mul_f32_e32 v100, s7, v80
	v_mul_f32_e32 v101, s7, v81
	v_mul_f32_e32 v102, s7, v82
	v_mul_f32_e32 v103, s7, v83
	v_mov_b32_e32 v104, v88
	v_mov_b32_e32 v105, v89
.Ltr_mvdone:
	v_cndmask_b32_e64 v96, 0, v96, s[10:11]
	v_cndmask_b32_e64 v97, 0, v97, s[10:11]
	v_cndmask_b32_e64 v98, 0, v98, s[10:11]
	v_cndmask_b32_e64 v99, 0, v99, s[10:11]
	v_cndmask_b32_e64 v100, 0, v100, s[10:11]
	v_cndmask_b32_e64 v101, 0, v101, s[10:11]
	v_cndmask_b32_e64 v102, 0, v102, s[10:11]
	v_cndmask_b32_e64 v103, 0, v103, s[10:11]
	v_mul_u32_u24_e32 v106, 0x110, v41
	v_add3_u32 v106, v106, v42, s101
	ds_write_b128 v106, v[96:99]
	ds_write_b128 v106, v[100:103] offset:8704
	v_lshlrev_b32_e32 v47, 3, v40
	v_and_b32_e32 v47, 56, v47
	v_mul_u32_u24_e32 v107, 0x110, v47
	v_lshlrev_b32_e32 v48, 2, v44
	v_add3_u32 v107, v107, v48, s101
	v_add_u32_e32 v108, 0x400, v107
	s_waitcnt lgkmcnt(0)
	s_barrier
	ds_read2_b32 v[110:111], v107 offset1:68
	ds_read2_b32 v[112:113], v107 offset0:136 offset1:204
	ds_read2_b32 v[114:115], v108 offset0:16 offset1:84
	ds_read2_b32 v[116:117], v108 offset0:152 offset1:220
	s_xor_b32 s101, s101, 0x4400
	s_add_i32 s99, s99, 1
	s_cmp_ge_u32 s99, 3
	s_cselect_b32 s99, 0, s99
	s_min_u32 s98, s98, 1
	s_add_i32 s98, s98, 1
	s_waitcnt lgkmcnt(3)
	v_cvt_pk_bf16_f32 v118, v110, v111
	s_waitcnt lgkmcnt(2)
	v_cvt_pk_bf16_f32 v119, v112, v113
	s_waitcnt lgkmcnt(1)
	v_cvt_pk_bf16_f32 v120, v114, v115
	s_waitcnt lgkmcnt(0)
	v_cvt_pk_bf16_f32 v121, v116, v117
	global_store_dwordx4 v[104:105], v[118:121], off

	.amdhsa_kernel _Z8mega_fwd6Params
		.amdhsa_group_segment_fixed_size 0
		.amdhsa_private_segment_fixed_size 0
		.amdhsa_kernarg_size 440
		.amdhsa_user_sgpr_count 2
		.amdhsa_user_sgpr_dispatch_ptr 0
		.amdhsa_user_sgpr_queue_ptr 0
		.amdhsa_user_sgpr_kernarg_segment_ptr 1
		.amdhsa_user_sgpr_dispatch_id 0
		.amdhsa_user_sgpr_kernarg_preload_length 0
		.amdhsa_user_sgpr_kernarg_preload_offset 0
		.amdhsa_user_sgpr_private_segment_size 0
		.amdhsa_uses_dynamic_stack 0
		.amdhsa_enable_private_segment 0
		.amdhsa_system_sgpr_workgroup_id_x 1
		.amdhsa_system_sgpr_workgroup_id_y 0
		.amdhsa_system_sgpr_workgroup_id_z 0
		.amdhsa_system_sgpr_workgroup_info 0
		.amdhsa_system_vgpr_workitem_id 2
		.amdhsa_next_free_vgpr 251
		.amdhsa_next_free_sgpr 102
		.amdhsa_accum_offset 252
		.amdhsa_reserve_vcc 1
		.amdhsa_float_round_mode_32 0
		.amdhsa_float_round_mode_16_64 0
		.amdhsa_float_denorm_mode_32 3
		.amdhsa_float_denorm_mode_16_64 3
		.amdhsa_dx10_clamp 1
		.amdhsa_ieee_mode 1
		.amdhsa_fp16_overflow 0
		.amdhsa_tg_split 0
		.amdhsa_exception_fp_ieee_invalid_op 0
		.amdhsa_exception_fp_denorm_src 0
		.amdhsa_exception_fp_ieee_div_zero 0
		.amdhsa_exception_fp_ieee_overflow 0
		.amdhsa_exception_fp_ieee_underflow 0
		.amdhsa_exception_fp_ieee_inexact 0
		.amdhsa_exception_int_div_zero 0
	.end_amdhsa_kernel

amdhsa.kernels:
  - .agpr_count:     0
    .args:
      - .offset:         0
        .size:           184
        .value_kind:     by_value
      - .offset:         184
        .size:           4
        .value_kind:     hidden_block_count_x
      - .offset:         188
        .size:           4
        .value_kind:     hidden_block_count_y
      - .offset:         192
        .size:           4
        .value_kind:     hidden_block_count_z
      - .offset:         196
        .size:           2
        .value_kind:     hidden_group_size_x
      - .offset:         198
        .size:           2
        .value_kind:     hidden_group_size_y
      - .offset:         200
        .size:           2
        .value_kind:     hidden_group_size_z
      - .offset:         202
        .size:           2
        .value_kind:     hidden_remainder_x
      - .offset:         204
        .size:           2
        .value_kind:     hidden_remainder_y
      - .offset:         206
        .size:           2
        .value_kind:     hidden_remainder_z
      - .offset:         224
        .size:           8
        .value_kind:     hidden_global_offset_x
      - .offset:         232
        .size:           8
        .value_kind:     hidden_global_offset_y
      - .offset:         240
        .size:           8
        .value_kind:     hidden_global_offset_z
      - .offset:         248
        .size:           2
        .value_kind:     hidden_grid_dims
      - .offset:         272
        .size:           8
        .value_kind:     hidden_multigrid_sync_arg
      - .offset:         304
        .size:           4
        .value_kind:     hidden_dynamic_lds_size
    .group_segment_fixed_size: 0
    .kernarg_segment_align: 8
    .kernarg_segment_size: 440
    .language:       OpenCL C
    .language_version:
      - 2
      - 0
    .max_flat_workgroup_size: 512
    .name:           _Z8mega_fwd6Params
    .private_segment_fixed_size: 0
    .sgpr_count:     108
    .sgpr_spill_count: 9
    .symbol:         _Z8mega_fwd6Params.kd
    .uniform_work_group_size: 1
    .uses_dynamic_stack: false
    .vgpr_count:     251
    .vgpr_spill_count: 0
    .wavefront_size: 64
